# stream-update loops: wave-sum butterfly steps via v_permlane32_swap and DPP (row_ror/row_shl/shr/quad_perm) instead of ds_bpermute round trips, same reduction tree
# speedup vs baseline: 1.0057x; 1.0023x over previous
.Le00_p0:
	v_mul_f32_e32 v41, v7, v7
	v_fmac_f32_e32 v41, v6, v6
	v_fmac_f32_e32 v41, v8, v8
	v_fmac_f32_e32 v41, v9, v9
	v_fmac_f32_e32 v41, v10, v10
	v_fmac_f32_e32 v41, v11, v11
	v_fmac_f32_e32 v41, v12, v12
	v_fmac_f32_e32 v41, v13, v13
	v_fmac_f32_e32 v41, v14, v14
	v_fmac_f32_e32 v41, v15, v15
	v_fmac_f32_e32 v41, v16, v16
	v_fmac_f32_e32 v41, v17, v17
	v_fmac_f32_e32 v41, v18, v18
	v_fmac_f32_e32 v41, v19, v19
	v_fmac_f32_e32 v41, v20, v20
	v_fmac_f32_e32 v41, v21, v21
	s_mov_b32 s98, 0
	s_mov_b32 s99, -1
	v_mov_b32_e32 v250, v41
	v_mov_b32_e32 v49, v41
	s_nop 3
	v_permlane32_swap_b32_e32 v49, v250
	v_cndmask_b32_e64 v49, v250, v49, s[98:99]
	v_cvt_pk_bf16_f32 v51, v8, v9
	v_cvt_pk_bf16_f32 v52, v10, v11
	s_waitcnt lgkmcnt(0)
	v_add_f32_e32 v41, v41, v49
	ds_bpermute_b32 v49, v43, v41
	s_waitcnt lgkmcnt(0)
	v_add_f32_e32 v49, v41, v49
	s_nop 1
	v_mov_b32_dpp v50, v49 row_ror:8 row_mask:0xf bank_mask:0xf
	v_ashrrev_i32_e32 v41, 31, v40
	v_lshlrev_b64 v[54:55], 11, v[40:41]
	v_lshl_add_u64 v[56:57], v[34:35], 0, v[54:55]
	v_cvt_pk_bf16_f32 v54, v18, v19
	s_waitcnt lgkmcnt(0)
	v_add_f32_e32 v49, v49, v50
	s_nop 1
	v_mov_b32_dpp v53, v49 row_shl:4 row_mask:0xf bank_mask:0x5
	v_mov_b32_dpp v53, v49 row_shr:4 row_mask:0xf bank_mask:0xa
	v_cvt_pk_bf16_f32 v50, v6, v7
	v_cvt_pk_bf16_f32 v55, v20, v21
	s_waitcnt lgkmcnt(0)
	v_add_f32_e32 v49, v49, v53
	s_nop 1
	v_mov_b32_dpp v58, v49 quad_perm:[2,3,0,1] row_mask:0xf bank_mask:0xf
	v_cvt_pk_bf16_f32 v53, v12, v13
	global_store_dwordx4 v[56:57], v[50:53], off
	s_waitcnt lgkmcnt(0)
	v_add_f32_e32 v49, v49, v58
	s_nop 1
	v_mov_b32_dpp v50, v49 quad_perm:[1,0,3,2] row_mask:0xf bank_mask:0xf
	v_cvt_pk_bf16_f32 v52, v14, v15
	v_cvt_pk_bf16_f32 v53, v16, v17
	global_store_dwordx4 v[56:57], v[52:55], off offset:1024
	s_and_saveexec_b64 s[14:15], vcc
	s_cbranch_execz .LBB0_125
	s_waitcnt lgkmcnt(0)
	v_add_f32_e32 v49, v49, v50
	v_fmamk_f32 v49, v49, 0x3a800000, v48
	v_mul_f32_e32 v50, 0x4b800000, v49
	v_cmp_gt_f32_e64 s[6:7], s19, v49
	s_nop 1
	v_cndmask_b32_e64 v49, v49, v50, s[6:7]
	v_rsq_f32_e32 v49, v49
	s_nop 0
	v_mul_f32_e32 v50, 0x45800000, v49
	v_cndmask_b32_e64 v49, v49, v50, s[6:7]
	v_lshl_add_u64 v[50:51], v[40:41], 2, s[10:11]
	global_store_dword v[50:51], v49, off

.Le00_p1:
	v_mul_f32_e32 v40, v3, v3
	v_fmac_f32_e32 v40, v2, v2
	v_fmac_f32_e32 v40, v4, v4
	v_fmac_f32_e32 v40, v5, v5
	v_fmac_f32_e32 v40, v22, v22
	v_fmac_f32_e32 v40, v23, v23
	v_fmac_f32_e32 v40, v24, v24
	v_fmac_f32_e32 v40, v25, v25
	v_fmac_f32_e32 v40, v30, v30
	v_fmac_f32_e32 v40, v31, v31
	v_fmac_f32_e32 v40, v32, v32
	v_fmac_f32_e32 v40, v33, v33
	v_fmac_f32_e32 v40, v26, v26
	v_fmac_f32_e32 v40, v27, v27
	v_fmac_f32_e32 v40, v28, v28
	v_fmac_f32_e32 v40, v29, v29
	s_mov_b32 s98, 0
	s_mov_b32 s99, -1
	v_mov_b32_e32 v250, v40
	v_mov_b32_e32 v41, v40
	s_nop 3
	v_permlane32_swap_b32_e32 v41, v250
	v_cndmask_b32_e64 v41, v250, v41, s[98:99]
	s_waitcnt lgkmcnt(1)
	v_cvt_pk_bf16_f32 v50, v2, v3
	v_cvt_pk_bf16_f32 v51, v4, v5
	v_cvt_pk_bf16_f32 v52, v22, v23
	s_waitcnt lgkmcnt(0)
	v_add_f32_e32 v40, v40, v41
	ds_bpermute_b32 v41, v43, v40
	s_waitcnt lgkmcnt(0)
	v_add_f32_e32 v40, v40, v41
	s_nop 1
	v_mov_b32_dpp v41, v40 row_ror:8 row_mask:0xf bank_mask:0xf
	s_waitcnt lgkmcnt(0)
	v_add_f32_e32 v49, v40, v41
	s_nop 1
	v_mov_b32_dpp v53, v49 row_shl:4 row_mask:0xf bank_mask:0x5
	v_mov_b32_dpp v53, v49 row_shr:4 row_mask:0xf bank_mask:0xa
	v_lshlrev_b64 v[40:41], 11, v[38:39]
	v_lshl_add_u64 v[54:55], v[34:35], 0, v[40:41]
	s_waitcnt lgkmcnt(0)
	v_add_f32_e32 v49, v49, v53
	s_nop 1
	v_mov_b32_dpp v56, v49 quad_perm:[2,3,0,1] row_mask:0xf bank_mask:0xf
	v_cvt_pk_bf16_f32 v53, v24, v25
	global_store_dwordx4 v[54:55], v[50:53], off
	s_waitcnt lgkmcnt(0)
	v_add_f32_e32 v40, v49, v56
	s_nop 1
	v_mov_b32_dpp v41, v40 quad_perm:[1,0,3,2] row_mask:0xf bank_mask:0xf
	v_cvt_pk_bf16_f32 v50, v30, v31
	v_cvt_pk_bf16_f32 v51, v32, v33
	v_cvt_pk_bf16_f32 v52, v26, v27
	v_cvt_pk_bf16_f32 v53, v28, v29
	global_store_dwordx4 v[54:55], v[50:53], off offset:1024
	s_and_saveexec_b64 s[14:15], vcc
	s_cbranch_execz .LBB0_119
	s_waitcnt lgkmcnt(0)
	v_add_f32_e32 v40, v40, v41
	v_fmamk_f32 v40, v40, 0x3a800000, v48
	v_mul_f32_e32 v41, 0x4b800000, v40
	v_cmp_gt_f32_e64 s[4:5], s19, v40
	s_nop 1
	v_cndmask_b32_e64 v40, v40, v41, s[4:5]
	v_rsq_f32_e32 v40, v40
	s_nop 0
	v_mul_f32_e32 v41, 0x45800000, v40
	v_cndmask_b32_e64 v49, v40, v41, s[4:5]
	v_lshl_add_u64 v[40:41], v[38:39], 2, s[10:11]
	global_store_dword v[40:41], v49, off
	s_branch .LBB0_119

.Le0_p1:
	s_mov_b32 s98, 0
	s_mov_b32 s99, -1
	v_mov_b32_e32 v250, v57
	v_mov_b32_e32 v55, v57
	s_nop 3
	v_permlane32_swap_b32_e32 v55, v250
	v_cndmask_b32_e64 v55, v250, v55, s[98:99]
	v_lshlrev_b32_e32 v70, 16, v24
	v_and_b32_e32 v71, 0xffff0000, v24
	v_lshlrev_b32_e32 v68, 16, v16
	v_and_b32_e32 v69, 0xffff0000, v16
	s_waitcnt lgkmcnt(0)
	v_add_f32_e32 v55, v57, v55
	ds_bpermute_b32 v65, v59, v55
	v_lshlrev_b32_e32 v72, 16, v25
	v_and_b32_e32 v73, 0xffff0000, v25
	v_lshlrev_b32_e32 v74, 16, v26
	v_and_b32_e32 v75, 0xffff0000, v26
	s_waitcnt lgkmcnt(0)
	v_add_f32_e32 v55, v55, v65
	s_nop 1
	v_mov_b32_dpp v65, v55 row_ror:8 row_mask:0xf bank_mask:0xf
	v_lshlrev_b32_e32 v76, 16, v27
	v_and_b32_e32 v77, 0xffff0000, v27
	v_lshlrev_b32_e32 v78, 16, v28
	v_and_b32_e32 v79, 0xffff0000, v28
	s_waitcnt lgkmcnt(0)
	v_add_f32_e32 v55, v55, v65
	s_nop 1
	v_mov_b32_dpp v65, v55 row_shl:4 row_mask:0xf bank_mask:0x5
	v_mov_b32_dpp v65, v55 row_shr:4 row_mask:0xf bank_mask:0xa
	v_lshlrev_b32_e32 v80, 16, v29
	v_and_b32_e32 v81, 0xffff0000, v29
	v_lshlrev_b32_e32 v82, 16, v30
	v_and_b32_e32 v83, 0xffff0000, v30
	s_waitcnt lgkmcnt(0)
	v_add_f32_e32 v55, v55, v65
	s_nop 1
	v_mov_b32_dpp v65, v55 quad_perm:[2,3,0,1] row_mask:0xf bank_mask:0xf
	v_lshlrev_b32_e32 v84, 16, v31
	v_and_b32_e32 v85, 0xffff0000, v31
	s_waitcnt lgkmcnt(0)
	v_add_f32_e32 v55, v55, v65
	s_nop 1
	v_mov_b32_dpp v65, v55 quad_perm:[1,0,3,2] row_mask:0xf bank_mask:0xf
	s_waitcnt lgkmcnt(0)
	v_add_f32_e32 v55, v55, v65
	v_fmamk_f32 v55, v55, 0x3a800000, v156
	v_cmp_gt_f32_e64 s[12:13], s28, v55
	v_mul_f32_e32 v65, 0x4b800000, v55
	s_nop 0
	v_cndmask_b32_e64 v55, v55, v65, s[12:13]
	v_rsq_f32_e32 v55, v55
	s_nop 0
	v_mul_f32_e32 v65, 0x45800000, v55
	v_cndmask_b32_e64 v66, v55, v65, s[12:13]
	v_pk_mul_f32 v[70:71], v[66:67], v[70:71] op_sel_hi:[0,1]
	v_pk_fma_f32 v[70:71], v[4:5], v[70:71], v[68:69]
	v_lshlrev_b32_e32 v68, 16, v17
	v_and_b32_e32 v69, 0xffff0000, v17
	v_pk_mul_f32 v[72:73], v[66:67], v[72:73] op_sel_hi:[0,1]
	v_pk_fma_f32 v[72:73], v[6:7], v[72:73], v[68:69]
	v_lshlrev_b32_e32 v68, 16, v18
	v_and_b32_e32 v69, 0xffff0000, v18
	v_pk_mul_f32 v[74:75], v[66:67], v[74:75] op_sel_hi:[0,1]
	v_pk_fma_f32 v[74:75], v[0:1], v[74:75], v[68:69]
	v_lshlrev_b32_e32 v68, 16, v19
	v_and_b32_e32 v69, 0xffff0000, v19
	v_pk_mul_f32 v[76:77], v[66:67], v[76:77] op_sel_hi:[0,1]
	v_pk_fma_f32 v[76:77], v[2:3], v[76:77], v[68:69]
	v_lshlrev_b32_e32 v68, 16, v20
	v_and_b32_e32 v69, 0xffff0000, v20
	v_pk_mul_f32 v[78:79], v[66:67], v[78:79] op_sel_hi:[0,1]
	v_pk_fma_f32 v[78:79], v[12:13], v[78:79], v[68:69]
	v_lshlrev_b32_e32 v68, 16, v21
	v_and_b32_e32 v69, 0xffff0000, v21
	v_pk_mul_f32 v[80:81], v[66:67], v[80:81] op_sel_hi:[0,1]
	v_pk_fma_f32 v[80:81], v[14:15], v[80:81], v[68:69]
	v_lshlrev_b32_e32 v68, 16, v22
	v_and_b32_e32 v69, 0xffff0000, v22
	v_pk_mul_f32 v[82:83], v[66:67], v[82:83] op_sel_hi:[0,1]
	v_pk_fma_f32 v[82:83], v[8:9], v[82:83], v[68:69]
	v_lshlrev_b32_e32 v68, 16, v23
	v_and_b32_e32 v69, 0xffff0000, v23
	v_pk_mul_f32 v[66:67], v[66:67], v[84:85] op_sel_hi:[0,1]
	v_pk_fma_f32 v[84:85], v[10:11], v[66:67], v[68:69]
	v_cvt_pk_bf16_f32 v66, v70, v71
	v_pk_mul_f32 v[70:71], v[70:71], v[70:71]
	v_cvt_pk_bf16_f32 v67, v72, v73
	v_pk_mul_f32 v[72:73], v[72:73], v[72:73]
	v_add_f32_e32 v65, v70, v71
	v_add_f32_e32 v65, v72, v65
	v_cvt_pk_bf16_f32 v68, v74, v75
	v_pk_mul_f32 v[74:75], v[74:75], v[74:75]
	v_add_f32_e32 v65, v73, v65
	v_ashrrev_i32_e32 v55, 31, v54
	v_add_f32_e32 v65, v74, v65
	v_lshlrev_b64 v[86:87], 11, v[54:55]
	v_cvt_pk_bf16_f32 v69, v76, v77
	v_pk_mul_f32 v[76:77], v[76:77], v[76:77]
	v_add_f32_e32 v65, v75, v65
	v_lshl_add_u64 v[86:87], v[48:49], 0, v[86:87]
	v_add_f32_e32 v65, v76, v65
	global_store_dwordx4 v[86:87], v[66:69], off
	v_add_f32_e32 v65, v77, v65
	s_nop 0
	v_cvt_pk_bf16_f32 v66, v78, v79
	v_pk_mul_f32 v[78:79], v[78:79], v[78:79]
	v_cvt_pk_bf16_f32 v67, v80, v81
	v_add_f32_e32 v65, v78, v65
	v_pk_mul_f32 v[80:81], v[80:81], v[80:81]
	v_add_f32_e32 v65, v79, v65
	v_add_f32_e32 v65, v80, v65
	v_cvt_pk_bf16_f32 v68, v82, v83
	v_pk_mul_f32 v[82:83], v[82:83], v[82:83]
	v_add_f32_e32 v65, v81, v65
	v_add_f32_e32 v65, v82, v65
	v_cvt_pk_bf16_f32 v69, v84, v85
	v_pk_mul_f32 v[84:85], v[84:85], v[84:85]
	v_add_f32_e32 v65, v83, v65
	v_add_f32_e32 v65, v84, v65
	v_add_f32_e32 v65, v85, v65
	global_store_dwordx4 v[86:87], v[66:69], off offset:1024
	s_mov_b32 s98, 0
	s_mov_b32 s99, -1
	v_mov_b32_e32 v250, v65
	v_mov_b32_e32 v66, v65
	s_nop 3
	v_permlane32_swap_b32_e32 v66, v250
	v_cndmask_b32_e64 v66, v250, v66, s[98:99]
	s_waitcnt lgkmcnt(0)
	v_add_f32_e32 v65, v65, v66
	ds_bpermute_b32 v66, v59, v65
	s_waitcnt lgkmcnt(0)
	v_add_f32_e32 v65, v65, v66
	s_nop 1
	v_mov_b32_dpp v66, v65 row_ror:8 row_mask:0xf bank_mask:0xf
	s_waitcnt lgkmcnt(0)
	v_add_f32_e32 v65, v65, v66
	s_nop 1
	v_mov_b32_dpp v66, v65 row_shl:4 row_mask:0xf bank_mask:0x5
	v_mov_b32_dpp v66, v65 row_shr:4 row_mask:0xf bank_mask:0xa
	s_waitcnt lgkmcnt(0)
	v_add_f32_e32 v65, v65, v66
	s_nop 1
	v_mov_b32_dpp v66, v65 quad_perm:[2,3,0,1] row_mask:0xf bank_mask:0xf
	s_waitcnt lgkmcnt(0)
	v_add_f32_e32 v65, v65, v66
	s_nop 1
	v_mov_b32_dpp v66, v65 quad_perm:[1,0,3,2] row_mask:0xf bank_mask:0xf
	s_and_saveexec_b64 s[6:7], s[8:9]
	s_cbranch_execz .LBB0_638
	s_waitcnt lgkmcnt(0)
	v_add_f32_e32 v65, v65, v66
	v_fmamk_f32 v65, v65, 0x3a800000, v156
	v_mul_f32_e32 v66, 0x4b800000, v65
	v_cmp_gt_f32_e64 s[12:13], s28, v65
	s_nop 1
	v_cndmask_b32_e64 v65, v65, v66, s[12:13]
	v_rsq_f32_e32 v65, v65
	s_nop 0
	v_mul_f32_e32 v66, 0x45800000, v65
	v_cndmask_b32_e64 v65, v65, v66, s[12:13]
	v_lshl_add_u64 v[66:67], v[54:55], 2, s[38:39]
	global_store_dword v[66:67], v65, off

.Le0_p2:
	s_mov_b32 s98, 0
	s_mov_b32 s99, -1
	v_mov_b32_e32 v250, v64
	v_mov_b32_e32 v54, v64
	s_nop 3
	v_permlane32_swap_b32_e32 v54, v250
	v_cndmask_b32_e64 v54, v250, v54, s[98:99]
	v_lshlrev_b32_e32 v68, 16, v44
	v_and_b32_e32 v69, 0xffff0000, v44
	s_waitcnt lgkmcnt(1)
	v_lshlrev_b32_e32 v66, 16, v32
	v_and_b32_e32 v67, 0xffff0000, v32
	s_waitcnt lgkmcnt(0)
	v_add_f32_e32 v54, v64, v54
	ds_bpermute_b32 v55, v59, v54
	v_lshlrev_b64 v[84:85], 11, v[52:53]
	v_lshl_add_u64 v[84:85], v[48:49], 0, v[84:85]
	s_waitcnt lgkmcnt(0)
	v_add_f32_e32 v54, v54, v55
	s_nop 1
	v_mov_b32_dpp v55, v54 row_ror:8 row_mask:0xf bank_mask:0xf
	s_waitcnt lgkmcnt(0)
	v_add_f32_e32 v54, v54, v55
	s_nop 1
	v_mov_b32_dpp v55, v54 row_shl:4 row_mask:0xf bank_mask:0x5
	v_mov_b32_dpp v55, v54 row_shr:4 row_mask:0xf bank_mask:0xa
	s_waitcnt lgkmcnt(0)
	v_add_f32_e32 v54, v54, v55
	s_nop 1
	v_mov_b32_dpp v55, v54 quad_perm:[2,3,0,1] row_mask:0xf bank_mask:0xf
	s_waitcnt lgkmcnt(0)
	v_add_f32_e32 v54, v54, v55
	s_nop 1
	v_mov_b32_dpp v55, v54 quad_perm:[1,0,3,2] row_mask:0xf bank_mask:0xf
	s_waitcnt lgkmcnt(0)
	v_add_f32_e32 v54, v54, v55
	v_fmamk_f32 v54, v54, 0x3a800000, v156
	v_cmp_gt_f32_e64 s[10:11], s28, v54
	v_mul_f32_e32 v55, 0x4b800000, v54
	s_nop 0
	v_cndmask_b32_e64 v54, v54, v55, s[10:11]
	v_rsq_f32_e32 v54, v54
	s_nop 0
	v_mul_f32_e32 v55, 0x45800000, v54
	v_cndmask_b32_e64 v54, v54, v55, s[10:11]
	v_pk_mul_f32 v[68:69], v[54:55], v[68:69] op_sel_hi:[0,1]
	v_pk_fma_f32 v[70:71], v[4:5], v[68:69], v[66:67]
	v_lshlrev_b32_e32 v68, 16, v45
	v_and_b32_e32 v69, 0xffff0000, v45
	v_lshlrev_b32_e32 v66, 16, v33
	v_and_b32_e32 v67, 0xffff0000, v33
	v_pk_mul_f32 v[68:69], v[54:55], v[68:69] op_sel_hi:[0,1]
	v_pk_fma_f32 v[72:73], v[6:7], v[68:69], v[66:67]
	v_lshlrev_b32_e32 v68, 16, v46
	v_and_b32_e32 v69, 0xffff0000, v46
	v_lshlrev_b32_e32 v66, 16, v34
	v_and_b32_e32 v67, 0xffff0000, v34
	v_pk_mul_f32 v[68:69], v[54:55], v[68:69] op_sel_hi:[0,1]
	v_pk_fma_f32 v[74:75], v[0:1], v[68:69], v[66:67]
	v_lshlrev_b32_e32 v68, 16, v47
	v_and_b32_e32 v69, 0xffff0000, v47
	v_lshlrev_b32_e32 v66, 16, v35
	v_and_b32_e32 v67, 0xffff0000, v35
	v_pk_mul_f32 v[68:69], v[54:55], v[68:69] op_sel_hi:[0,1]
	v_pk_fma_f32 v[76:77], v[2:3], v[68:69], v[66:67]
	v_lshlrev_b32_e32 v68, 16, v40
	v_and_b32_e32 v69, 0xffff0000, v40
	v_lshlrev_b32_e32 v66, 16, v36
	v_and_b32_e32 v67, 0xffff0000, v36
	v_pk_mul_f32 v[68:69], v[54:55], v[68:69] op_sel_hi:[0,1]
	v_pk_fma_f32 v[78:79], v[12:13], v[68:69], v[66:67]
	v_lshlrev_b32_e32 v68, 16, v41
	v_and_b32_e32 v69, 0xffff0000, v41
	v_lshlrev_b32_e32 v66, 16, v37
	v_and_b32_e32 v67, 0xffff0000, v37
	v_pk_mul_f32 v[68:69], v[54:55], v[68:69] op_sel_hi:[0,1]
	v_pk_fma_f32 v[80:81], v[14:15], v[68:69], v[66:67]
	v_lshlrev_b32_e32 v68, 16, v42
	v_and_b32_e32 v69, 0xffff0000, v42
	v_lshlrev_b32_e32 v66, 16, v38
	v_and_b32_e32 v67, 0xffff0000, v38
	v_pk_mul_f32 v[68:69], v[54:55], v[68:69] op_sel_hi:[0,1]
	v_pk_fma_f32 v[82:83], v[8:9], v[68:69], v[66:67]
	v_lshlrev_b32_e32 v68, 16, v43
	v_and_b32_e32 v69, 0xffff0000, v43
	v_lshlrev_b32_e32 v66, 16, v39
	v_and_b32_e32 v67, 0xffff0000, v39
	v_pk_mul_f32 v[54:55], v[54:55], v[68:69] op_sel_hi:[0,1]
	v_pk_fma_f32 v[54:55], v[10:11], v[54:55], v[66:67]
	v_cvt_pk_bf16_f32 v66, v70, v71
	v_pk_mul_f32 v[70:71], v[70:71], v[70:71]
	v_cvt_pk_bf16_f32 v67, v72, v73
	v_pk_mul_f32 v[72:73], v[72:73], v[72:73]
	v_add_f32_e32 v65, v70, v71
	v_add_f32_e32 v65, v72, v65
	v_cvt_pk_bf16_f32 v68, v74, v75
	v_pk_mul_f32 v[74:75], v[74:75], v[74:75]
	v_add_f32_e32 v65, v73, v65
	v_add_f32_e32 v65, v74, v65
	v_cvt_pk_bf16_f32 v69, v76, v77
	v_pk_mul_f32 v[76:77], v[76:77], v[76:77]
	v_add_f32_e32 v65, v75, v65
	v_add_f32_e32 v65, v76, v65
	global_store_dwordx4 v[84:85], v[66:69], off
	v_add_f32_e32 v65, v77, v65
	s_nop 0
	v_cvt_pk_bf16_f32 v66, v78, v79
	v_pk_mul_f32 v[78:79], v[78:79], v[78:79]
	v_cvt_pk_bf16_f32 v67, v80, v81
	v_add_f32_e32 v65, v78, v65
	v_pk_mul_f32 v[80:81], v[80:81], v[80:81]
	v_add_f32_e32 v65, v79, v65
	v_add_f32_e32 v65, v80, v65
	v_cvt_pk_bf16_f32 v68, v82, v83
	v_pk_mul_f32 v[82:83], v[82:83], v[82:83]
	v_add_f32_e32 v65, v81, v65
	v_add_f32_e32 v65, v82, v65
	v_cvt_pk_bf16_f32 v69, v54, v55
	v_pk_mul_f32 v[54:55], v[54:55], v[54:55]
	v_add_f32_e32 v65, v83, v65
	v_add_f32_e32 v54, v54, v65
	v_add_f32_e32 v54, v55, v54
	s_mov_b32 s98, 0
	s_mov_b32 s99, -1
	v_mov_b32_e32 v250, v54
	v_mov_b32_e32 v55, v54
	s_nop 3
	v_permlane32_swap_b32_e32 v55, v250
	v_cndmask_b32_e64 v55, v250, v55, s[98:99]
	global_store_dwordx4 v[84:85], v[66:69], off offset:1024
	s_waitcnt lgkmcnt(0)
	v_add_f32_e32 v54, v54, v55
	ds_bpermute_b32 v55, v59, v54
	s_waitcnt lgkmcnt(0)
	v_add_f32_e32 v54, v54, v55
	s_nop 1
	v_mov_b32_dpp v55, v54 row_ror:8 row_mask:0xf bank_mask:0xf
	s_waitcnt lgkmcnt(0)
	v_add_f32_e32 v54, v54, v55
	s_nop 1
	v_mov_b32_dpp v55, v54 row_shl:4 row_mask:0xf bank_mask:0x5
	v_mov_b32_dpp v55, v54 row_shr:4 row_mask:0xf bank_mask:0xa
	s_waitcnt lgkmcnt(0)
	v_add_f32_e32 v54, v54, v55
	s_nop 1
	v_mov_b32_dpp v55, v54 quad_perm:[2,3,0,1] row_mask:0xf bank_mask:0xf
	s_waitcnt lgkmcnt(0)
	v_add_f32_e32 v54, v54, v55
	s_nop 1
	v_mov_b32_dpp v55, v54 quad_perm:[1,0,3,2] row_mask:0xf bank_mask:0xf
	s_and_saveexec_b64 s[6:7], s[8:9]
	s_cbranch_execz .LBB0_630
	s_waitcnt lgkmcnt(0)
	v_add_f32_e32 v54, v54, v55
	v_fmamk_f32 v54, v54, 0x3a800000, v156
	v_mul_f32_e32 v55, 0x4b800000, v54
	v_cmp_gt_f32_e64 s[10:11], s28, v54
	s_nop 1
	v_cndmask_b32_e64 v54, v54, v55, s[10:11]
	v_rsq_f32_e32 v54, v54
	s_nop 0
	v_mul_f32_e32 v55, 0x45800000, v54
	v_cndmask_b32_e64 v65, v54, v55, s[10:11]
	v_lshl_add_u64 v[54:55], v[52:53], 2, s[38:39]
	global_store_dword v[54:55], v65, off
	s_branch .LBB0_630

.Le0_p3:
	s_mov_b32 s98, 0
	s_mov_b32 s99, -1
	v_mov_b32_e32 v250, v73
	v_mov_b32_e32 v71, v73
	s_nop 3
	v_permlane32_swap_b32_e32 v71, v250
	v_cndmask_b32_e64 v71, v250, v71, s[98:99]
	v_lshlrev_b32_e32 v84, 16, v32
	v_and_b32_e32 v85, 0xffff0000, v32
	s_waitcnt lgkmcnt(0)
	v_add_f32_e32 v71, v73, v71
	ds_bpermute_b32 v81, v75, v71
	s_waitcnt lgkmcnt(0)
	v_add_f32_e32 v71, v71, v81
	s_nop 1
	v_mov_b32_dpp v81, v71 row_ror:8 row_mask:0xf bank_mask:0xf
	s_waitcnt lgkmcnt(0)
	v_add_f32_e32 v71, v71, v81
	s_nop 1
	v_mov_b32_dpp v81, v71 row_shl:4 row_mask:0xf bank_mask:0x5
	v_mov_b32_dpp v81, v71 row_shr:4 row_mask:0xf bank_mask:0xa
	s_waitcnt lgkmcnt(0)
	v_add_f32_e32 v71, v71, v81
	s_nop 1
	v_mov_b32_dpp v81, v71 quad_perm:[2,3,0,1] row_mask:0xf bank_mask:0xf
	s_waitcnt lgkmcnt(0)
	v_add_f32_e32 v71, v71, v81
	s_nop 1
	v_mov_b32_dpp v81, v71 quad_perm:[1,0,3,2] row_mask:0xf bank_mask:0xf
	s_waitcnt lgkmcnt(0)
	v_add_f32_e32 v71, v71, v81
	v_fmamk_f32 v71, v71, 0x3a800000, v156
	v_cmp_gt_f32_e64 s[12:13], s28, v71
	v_mul_f32_e32 v81, 0x4b800000, v71
	s_nop 0
	v_cndmask_b32_e64 v71, v71, v81, s[12:13]
	v_rsq_f32_e32 v71, v71
	s_nop 0
	v_mul_f32_e32 v81, 0x45800000, v71
	v_cndmask_b32_e64 v82, v71, v81, s[12:13]
	v_pk_mul_f32 v[84:85], v[82:83], v[84:85] op_sel_hi:[0,1]
	v_pk_fma_f32 v[86:87], v[4:5], v[84:85], v[20:21]
	v_lshlrev_b32_e32 v84, 16, v33
	v_and_b32_e32 v85, 0xffff0000, v33
	v_pk_mul_f32 v[84:85], v[82:83], v[84:85] op_sel_hi:[0,1]
	v_pk_fma_f32 v[88:89], v[6:7], v[84:85], v[22:23]
	v_lshlrev_b32_e32 v84, 16, v34
	v_and_b32_e32 v85, 0xffff0000, v34
	v_pk_mul_f32 v[84:85], v[82:83], v[84:85] op_sel_hi:[0,1]
	v_pk_fma_f32 v[90:91], v[0:1], v[84:85], v[16:17]
	v_lshlrev_b32_e32 v84, 16, v35
	v_and_b32_e32 v85, 0xffff0000, v35
	v_pk_mul_f32 v[84:85], v[82:83], v[84:85] op_sel_hi:[0,1]
	v_pk_fma_f32 v[92:93], v[2:3], v[84:85], v[18:19]
	v_lshlrev_b32_e32 v84, 16, v36
	v_and_b32_e32 v85, 0xffff0000, v36
	v_pk_mul_f32 v[84:85], v[82:83], v[84:85] op_sel_hi:[0,1]
	v_pk_fma_f32 v[94:95], v[12:13], v[84:85], v[28:29]
	v_lshlrev_b32_e32 v84, 16, v37
	v_and_b32_e32 v85, 0xffff0000, v37
	v_pk_mul_f32 v[84:85], v[82:83], v[84:85] op_sel_hi:[0,1]
	v_pk_fma_f32 v[96:97], v[14:15], v[84:85], v[30:31]
	v_lshlrev_b32_e32 v84, 16, v38
	v_and_b32_e32 v85, 0xffff0000, v38
	v_pk_mul_f32 v[84:85], v[82:83], v[84:85] op_sel_hi:[0,1]
	v_pk_fma_f32 v[98:99], v[8:9], v[84:85], v[24:25]
	v_lshlrev_b32_e32 v84, 16, v39
	v_and_b32_e32 v85, 0xffff0000, v39
	v_pk_mul_f32 v[82:83], v[82:83], v[84:85] op_sel_hi:[0,1]
	v_pk_fma_f32 v[100:101], v[10:11], v[82:83], v[26:27]
	v_cvt_pk_bf16_f32 v82, v86, v87
	v_pk_mul_f32 v[86:87], v[86:87], v[86:87]
	v_cvt_pk_bf16_f32 v83, v88, v89
	v_pk_mul_f32 v[88:89], v[88:89], v[88:89]
	v_add_f32_e32 v81, v86, v87
	v_add_f32_e32 v81, v88, v81
	v_cvt_pk_bf16_f32 v84, v90, v91
	v_pk_mul_f32 v[90:91], v[90:91], v[90:91]
	v_add_f32_e32 v81, v89, v81
	v_ashrrev_i32_e32 v71, 31, v70
	v_add_f32_e32 v81, v90, v81
	v_lshlrev_b64 v[102:103], 11, v[70:71]
	v_cvt_pk_bf16_f32 v85, v92, v93
	v_pk_mul_f32 v[92:93], v[92:93], v[92:93]
	v_add_f32_e32 v81, v91, v81
	v_lshl_add_u64 v[102:103], v[64:65], 0, v[102:103]
	v_add_f32_e32 v81, v92, v81
	global_store_dwordx4 v[102:103], v[82:85], off
	v_add_f32_e32 v81, v93, v81
	s_nop 0
	v_cvt_pk_bf16_f32 v82, v94, v95
	v_pk_mul_f32 v[94:95], v[94:95], v[94:95]
	v_cvt_pk_bf16_f32 v83, v96, v97
	v_add_f32_e32 v81, v94, v81
	v_pk_mul_f32 v[96:97], v[96:97], v[96:97]
	v_add_f32_e32 v81, v95, v81
	v_add_f32_e32 v81, v96, v81
	v_cvt_pk_bf16_f32 v84, v98, v99
	v_pk_mul_f32 v[98:99], v[98:99], v[98:99]
	v_add_f32_e32 v81, v97, v81
	v_add_f32_e32 v81, v98, v81
	v_cvt_pk_bf16_f32 v85, v100, v101
	v_pk_mul_f32 v[100:101], v[100:101], v[100:101]
	v_add_f32_e32 v81, v99, v81
	v_add_f32_e32 v81, v100, v81
	v_add_f32_e32 v81, v101, v81
	global_store_dwordx4 v[102:103], v[82:85], off offset:1024
	s_mov_b32 s98, 0
	s_mov_b32 s99, -1
	v_mov_b32_e32 v250, v81
	v_mov_b32_e32 v82, v81
	s_nop 3
	v_permlane32_swap_b32_e32 v82, v250
	v_cndmask_b32_e64 v82, v250, v82, s[98:99]
	s_waitcnt lgkmcnt(0)
	v_add_f32_e32 v81, v81, v82
	ds_bpermute_b32 v82, v75, v81
	s_waitcnt lgkmcnt(0)
	v_add_f32_e32 v81, v81, v82
	s_nop 1
	v_mov_b32_dpp v82, v81 row_ror:8 row_mask:0xf bank_mask:0xf
	s_waitcnt lgkmcnt(0)
	v_add_f32_e32 v81, v81, v82
	s_nop 1
	v_mov_b32_dpp v82, v81 row_shl:4 row_mask:0xf bank_mask:0x5
	v_mov_b32_dpp v82, v81 row_shr:4 row_mask:0xf bank_mask:0xa
	s_waitcnt lgkmcnt(0)
	v_add_f32_e32 v81, v81, v82
	s_nop 1
	v_mov_b32_dpp v82, v81 quad_perm:[2,3,0,1] row_mask:0xf bank_mask:0xf
	s_waitcnt lgkmcnt(0)
	v_add_f32_e32 v81, v81, v82
	s_nop 1
	v_mov_b32_dpp v82, v81 quad_perm:[1,0,3,2] row_mask:0xf bank_mask:0xf
	s_and_saveexec_b64 s[6:7], s[8:9]
	s_cbranch_execz .LBB0_725
	s_waitcnt lgkmcnt(0)
	v_add_f32_e32 v81, v81, v82
	v_fmamk_f32 v81, v81, 0x3a800000, v156
	v_mul_f32_e32 v82, 0x4b800000, v81
	v_cmp_gt_f32_e64 s[12:13], s28, v81
	s_nop 1
	v_cndmask_b32_e64 v81, v81, v82, s[12:13]
	v_rsq_f32_e32 v81, v81
	s_nop 0
	v_mul_f32_e32 v82, 0x45800000, v81
	v_cndmask_b32_e64 v81, v81, v82, s[12:13]
	v_lshl_add_u64 v[82:83], v[70:71], 2, s[38:39]
	global_store_dword v[82:83], v81, off

.Le0_p4:
	s_mov_b32 s98, 0
	s_mov_b32 s99, -1
	v_mov_b32_e32 v250, v80
	v_mov_b32_e32 v70, v80
	s_nop 3
	v_permlane32_swap_b32_e32 v70, v250
	v_cndmask_b32_e64 v70, v250, v70, s[98:99]
	s_waitcnt lgkmcnt(1)
	v_lshlrev_b32_e32 v82, 16, v60
	v_and_b32_e32 v83, 0xffff0000, v60
	v_lshlrev_b64 v[100:101], 11, v[68:69]
	v_lshl_add_u64 v[100:101], v[64:65], 0, v[100:101]
	s_waitcnt lgkmcnt(0)
	v_add_f32_e32 v70, v80, v70
	ds_bpermute_b32 v71, v75, v70
	s_waitcnt lgkmcnt(0)
	v_add_f32_e32 v70, v70, v71
	s_nop 1
	v_mov_b32_dpp v71, v70 row_ror:8 row_mask:0xf bank_mask:0xf
	s_waitcnt lgkmcnt(0)
	v_add_f32_e32 v70, v70, v71
	s_nop 1
	v_mov_b32_dpp v71, v70 row_shl:4 row_mask:0xf bank_mask:0x5
	v_mov_b32_dpp v71, v70 row_shr:4 row_mask:0xf bank_mask:0xa
	s_waitcnt lgkmcnt(0)
	v_add_f32_e32 v70, v70, v71
	s_nop 1
	v_mov_b32_dpp v71, v70 quad_perm:[2,3,0,1] row_mask:0xf bank_mask:0xf
	s_waitcnt lgkmcnt(0)
	v_add_f32_e32 v70, v70, v71
	s_nop 1
	v_mov_b32_dpp v71, v70 quad_perm:[1,0,3,2] row_mask:0xf bank_mask:0xf
	s_waitcnt lgkmcnt(0)
	v_add_f32_e32 v70, v70, v71
	v_fmamk_f32 v70, v70, 0x3a800000, v156
	v_cmp_gt_f32_e64 s[10:11], s28, v70
	v_mul_f32_e32 v71, 0x4b800000, v70
	s_nop 0
	v_cndmask_b32_e64 v70, v70, v71, s[10:11]
	v_rsq_f32_e32 v70, v70
	s_nop 0
	v_mul_f32_e32 v71, 0x45800000, v70
	v_cndmask_b32_e64 v70, v70, v71, s[10:11]
	v_pk_mul_f32 v[82:83], v[70:71], v[82:83] op_sel_hi:[0,1]
	v_pk_fma_f32 v[86:87], v[4:5], v[82:83], v[52:53]
	v_lshlrev_b32_e32 v82, 16, v61
	v_and_b32_e32 v83, 0xffff0000, v61
	v_pk_mul_f32 v[82:83], v[70:71], v[82:83] op_sel_hi:[0,1]
	v_pk_fma_f32 v[88:89], v[6:7], v[82:83], v[54:55]
	v_lshlrev_b32_e32 v82, 16, v62
	v_and_b32_e32 v83, 0xffff0000, v62
	v_pk_mul_f32 v[82:83], v[70:71], v[82:83] op_sel_hi:[0,1]
	v_pk_fma_f32 v[90:91], v[0:1], v[82:83], v[44:45]
	v_lshlrev_b32_e32 v82, 16, v63
	v_and_b32_e32 v83, 0xffff0000, v63
	v_pk_mul_f32 v[82:83], v[70:71], v[82:83] op_sel_hi:[0,1]
	v_pk_fma_f32 v[92:93], v[2:3], v[82:83], v[46:47]
	v_lshlrev_b32_e32 v82, 16, v56
	v_and_b32_e32 v83, 0xffff0000, v56
	v_pk_mul_f32 v[82:83], v[70:71], v[82:83] op_sel_hi:[0,1]
	v_pk_fma_f32 v[94:95], v[12:13], v[82:83], v[48:49]
	v_lshlrev_b32_e32 v82, 16, v57
	v_and_b32_e32 v83, 0xffff0000, v57
	v_pk_mul_f32 v[82:83], v[70:71], v[82:83] op_sel_hi:[0,1]
	v_pk_fma_f32 v[96:97], v[14:15], v[82:83], v[50:51]
	v_lshlrev_b32_e32 v82, 16, v58
	v_and_b32_e32 v83, 0xffff0000, v58
	v_pk_mul_f32 v[82:83], v[70:71], v[82:83] op_sel_hi:[0,1]
	v_pk_fma_f32 v[98:99], v[8:9], v[82:83], v[40:41]
	v_lshlrev_b32_e32 v82, 16, v59
	v_and_b32_e32 v83, 0xffff0000, v59
	v_pk_mul_f32 v[70:71], v[70:71], v[82:83] op_sel_hi:[0,1]
	v_cvt_pk_bf16_f32 v82, v86, v87
	v_pk_mul_f32 v[86:87], v[86:87], v[86:87]
	v_cvt_pk_bf16_f32 v83, v88, v89
	v_pk_mul_f32 v[88:89], v[88:89], v[88:89]
	v_add_f32_e32 v81, v86, v87
	v_add_f32_e32 v81, v88, v81
	v_cvt_pk_bf16_f32 v84, v90, v91
	v_pk_mul_f32 v[90:91], v[90:91], v[90:91]
	v_add_f32_e32 v81, v89, v81
	v_add_f32_e32 v81, v90, v81
	v_cvt_pk_bf16_f32 v85, v92, v93
	v_pk_mul_f32 v[92:93], v[92:93], v[92:93]
	v_add_f32_e32 v81, v91, v81
	v_add_f32_e32 v81, v92, v81
	global_store_dwordx4 v[100:101], v[82:85], off
	v_add_f32_e32 v81, v93, v81
	v_pk_fma_f32 v[70:71], v[10:11], v[70:71], v[42:43]
	v_cvt_pk_bf16_f32 v82, v94, v95
	v_pk_mul_f32 v[94:95], v[94:95], v[94:95]
	v_cvt_pk_bf16_f32 v83, v96, v97
	v_add_f32_e32 v81, v94, v81
	v_pk_mul_f32 v[96:97], v[96:97], v[96:97]
	v_add_f32_e32 v81, v95, v81
	v_add_f32_e32 v81, v96, v81
	v_cvt_pk_bf16_f32 v84, v98, v99
	v_pk_mul_f32 v[98:99], v[98:99], v[98:99]
	v_add_f32_e32 v81, v97, v81
	v_add_f32_e32 v81, v98, v81
	v_cvt_pk_bf16_f32 v85, v70, v71
	v_pk_mul_f32 v[70:71], v[70:71], v[70:71]
	v_add_f32_e32 v81, v99, v81
	v_add_f32_e32 v70, v70, v81
	v_add_f32_e32 v70, v71, v70
	s_mov_b32 s98, 0
	s_mov_b32 s99, -1
	v_mov_b32_e32 v250, v70
	v_mov_b32_e32 v71, v70
	s_nop 3
	v_permlane32_swap_b32_e32 v71, v250
	v_cndmask_b32_e64 v71, v250, v71, s[98:99]
	global_store_dwordx4 v[100:101], v[82:85], off offset:1024
	s_waitcnt lgkmcnt(0)
	v_add_f32_e32 v70, v70, v71
	ds_bpermute_b32 v71, v75, v70
	s_waitcnt lgkmcnt(0)
	v_add_f32_e32 v70, v70, v71
	s_nop 1
	v_mov_b32_dpp v71, v70 row_ror:8 row_mask:0xf bank_mask:0xf
	s_waitcnt lgkmcnt(0)
	v_add_f32_e32 v70, v70, v71
	s_nop 1
	v_mov_b32_dpp v71, v70 row_shl:4 row_mask:0xf bank_mask:0x5
	v_mov_b32_dpp v71, v70 row_shr:4 row_mask:0xf bank_mask:0xa
	s_waitcnt lgkmcnt(0)
	v_add_f32_e32 v70, v70, v71
	s_nop 1
	v_mov_b32_dpp v71, v70 quad_perm:[2,3,0,1] row_mask:0xf bank_mask:0xf
	s_waitcnt lgkmcnt(0)
	v_add_f32_e32 v70, v70, v71
	s_nop 1
	v_mov_b32_dpp v71, v70 quad_perm:[1,0,3,2] row_mask:0xf bank_mask:0xf
	s_and_saveexec_b64 s[6:7], s[8:9]
	s_cbranch_execz .LBB0_717
	s_waitcnt lgkmcnt(0)
	v_add_f32_e32 v70, v70, v71
	v_fmamk_f32 v70, v70, 0x3a800000, v156
	v_mul_f32_e32 v71, 0x4b800000, v70
	v_cmp_gt_f32_e64 s[10:11], s28, v70
	s_nop 1
	v_cndmask_b32_e64 v70, v70, v71, s[10:11]
	v_rsq_f32_e32 v70, v70
	s_nop 0
	v_mul_f32_e32 v71, 0x45800000, v70
	v_cndmask_b32_e64 v81, v70, v71, s[10:11]
	v_lshl_add_u64 v[70:71], v[68:69], 2, s[38:39]
	global_store_dword v[70:71], v81, off
	s_branch .LBB0_717

.Le0_p8:
	s_mov_b32 s98, 0
	s_mov_b32 s99, -1
	v_mov_b32_e32 v250, v62
	v_mov_b32_e32 v52, v62
	s_nop 3
	v_permlane32_swap_b32_e32 v52, v250
	v_cndmask_b32_e64 v52, v250, v52, s[98:99]
	v_lshlrev_b32_e32 v66, 16, v44
	v_and_b32_e32 v67, 0xffff0000, v44
	v_lshlrev_b32_e32 v64, 16, v36
	v_and_b32_e32 v65, 0xffff0000, v36
	s_waitcnt lgkmcnt(0)
	v_add_f32_e32 v52, v62, v52
	ds_bpermute_b32 v53, v57, v52
	v_lshlrev_b32_e32 v68, 16, v45
	v_and_b32_e32 v69, 0xffff0000, v45
	v_lshlrev_b32_e32 v70, 16, v46
	v_and_b32_e32 v71, 0xffff0000, v46
	s_waitcnt lgkmcnt(0)
	v_add_f32_e32 v52, v52, v53
	s_nop 1
	v_mov_b32_dpp v53, v52 row_ror:8 row_mask:0xf bank_mask:0xf
	v_lshlrev_b32_e32 v72, 16, v47
	v_and_b32_e32 v73, 0xffff0000, v47
	v_lshlrev_b32_e32 v74, 16, v40
	v_and_b32_e32 v75, 0xffff0000, v40
	s_waitcnt lgkmcnt(0)
	v_add_f32_e32 v52, v52, v53
	s_nop 1
	v_mov_b32_dpp v53, v52 row_shl:4 row_mask:0xf bank_mask:0x5
	v_mov_b32_dpp v53, v52 row_shr:4 row_mask:0xf bank_mask:0xa
	v_lshlrev_b32_e32 v76, 16, v41
	v_and_b32_e32 v77, 0xffff0000, v41
	v_lshlrev_b32_e32 v78, 16, v42
	v_and_b32_e32 v79, 0xffff0000, v42
	s_waitcnt lgkmcnt(0)
	v_add_f32_e32 v52, v52, v53
	s_nop 1
	v_mov_b32_dpp v53, v52 quad_perm:[2,3,0,1] row_mask:0xf bank_mask:0xf
	v_lshlrev_b32_e32 v80, 16, v43
	v_and_b32_e32 v81, 0xffff0000, v43
	s_waitcnt lgkmcnt(0)
	v_add_f32_e32 v52, v52, v53
	s_nop 1
	v_mov_b32_dpp v53, v52 quad_perm:[1,0,3,2] row_mask:0xf bank_mask:0xf
	s_waitcnt lgkmcnt(0)
	v_add_f32_e32 v52, v52, v53
	v_fmamk_f32 v52, v52, 0x3a800000, v155
	v_cmp_gt_f32_e64 s[8:9], s69, v52
	v_mul_f32_e32 v53, 0x4b800000, v52
	s_nop 0
	v_cndmask_b32_e64 v52, v52, v53, s[8:9]
	v_rsq_f32_e32 v52, v52
	s_nop 0
	v_mul_f32_e32 v53, 0x45800000, v52
	v_cndmask_b32_e64 v52, v52, v53, s[8:9]
	v_pk_mul_f32 v[66:67], v[52:53], v[66:67] op_sel_hi:[0,1]
	v_pk_fma_f32 v[64:65], v[4:5], v[66:67], v[64:65]
	v_lshlrev_b32_e32 v66, 16, v37
	v_and_b32_e32 v67, 0xffff0000, v37
	v_pk_mul_f32 v[68:69], v[52:53], v[68:69] op_sel_hi:[0,1]
	v_pk_fma_f32 v[66:67], v[6:7], v[68:69], v[66:67]
	v_lshlrev_b32_e32 v68, 16, v38
	v_and_b32_e32 v69, 0xffff0000, v38
	v_pk_mul_f32 v[70:71], v[52:53], v[70:71] op_sel_hi:[0,1]
	v_pk_fma_f32 v[68:69], v[0:1], v[70:71], v[68:69]
	v_lshlrev_b32_e32 v70, 16, v39
	v_and_b32_e32 v71, 0xffff0000, v39
	v_pk_mul_f32 v[72:73], v[52:53], v[72:73] op_sel_hi:[0,1]
	v_pk_fma_f32 v[70:71], v[2:3], v[72:73], v[70:71]
	v_lshlrev_b32_e32 v72, 16, v32
	v_and_b32_e32 v73, 0xffff0000, v32
	v_pk_mul_f32 v[74:75], v[52:53], v[74:75] op_sel_hi:[0,1]
	v_pk_fma_f32 v[72:73], v[12:13], v[74:75], v[72:73]
	v_lshlrev_b32_e32 v74, 16, v33
	v_and_b32_e32 v75, 0xffff0000, v33
	v_pk_mul_f32 v[76:77], v[52:53], v[76:77] op_sel_hi:[0,1]
	v_pk_fma_f32 v[74:75], v[14:15], v[76:77], v[74:75]
	v_lshlrev_b32_e32 v76, 16, v34
	v_and_b32_e32 v77, 0xffff0000, v34
	v_pk_mul_f32 v[78:79], v[52:53], v[78:79] op_sel_hi:[0,1]
	v_pk_fma_f32 v[76:77], v[8:9], v[78:79], v[76:77]
	v_lshlrev_b32_e32 v78, 16, v35
	v_and_b32_e32 v79, 0xffff0000, v35
	v_pk_mul_f32 v[52:53], v[52:53], v[80:81] op_sel_hi:[0,1]
	v_pk_fma_f32 v[78:79], v[10:11], v[52:53], v[78:79]
	v_lshlrev_b64 v[52:53], 12, v[50:51]
	v_lshl_or_b32 v52, v54, 2, v52
	v_lshl_add_u64 v[52:53], s[86:87], 0, v[52:53]
	global_store_dwordx4 v[52:53], v[64:67], off
	global_store_dwordx4 v[52:53], v[68:71], off offset:16
	global_store_dwordx4 v[52:53], v[72:75], off offset:2048
	global_store_dwordx4 v[52:53], v[76:79], off offset:2064

.Le0_p7:
	s_mov_b32 s98, 0
	s_mov_b32 s99, -1
	v_mov_b32_e32 v250, v55
	v_mov_b32_e32 v53, v55
	s_nop 3
	v_permlane32_swap_b32_e32 v53, v250
	v_cndmask_b32_e64 v53, v250, v53, s[98:99]
	v_lshlrev_b32_e32 v66, 16, v24
	v_and_b32_e32 v67, 0xffff0000, v24
	v_lshlrev_b32_e32 v64, 16, v16
	v_and_b32_e32 v65, 0xffff0000, v16
	s_waitcnt lgkmcnt(0)
	v_add_f32_e32 v53, v55, v53
	ds_bpermute_b32 v63, v57, v53
	v_lshlrev_b32_e32 v68, 16, v25
	v_and_b32_e32 v69, 0xffff0000, v25
	v_lshlrev_b32_e32 v70, 16, v26
	v_and_b32_e32 v71, 0xffff0000, v26
	s_waitcnt lgkmcnt(0)
	v_add_f32_e32 v53, v53, v63
	s_nop 1
	v_mov_b32_dpp v63, v53 row_ror:8 row_mask:0xf bank_mask:0xf
	v_lshlrev_b32_e32 v72, 16, v27
	v_and_b32_e32 v73, 0xffff0000, v27
	v_lshlrev_b32_e32 v74, 16, v28
	v_and_b32_e32 v75, 0xffff0000, v28
	s_waitcnt lgkmcnt(0)
	v_add_f32_e32 v53, v53, v63
	s_nop 1
	v_mov_b32_dpp v63, v53 row_shl:4 row_mask:0xf bank_mask:0x5
	v_mov_b32_dpp v63, v53 row_shr:4 row_mask:0xf bank_mask:0xa
	v_lshlrev_b32_e32 v76, 16, v29
	v_and_b32_e32 v77, 0xffff0000, v29
	v_lshlrev_b32_e32 v80, 16, v30
	v_and_b32_e32 v81, 0xffff0000, v30
	s_waitcnt lgkmcnt(0)
	v_add_f32_e32 v53, v53, v63
	s_nop 1
	v_mov_b32_dpp v63, v53 quad_perm:[2,3,0,1] row_mask:0xf bank_mask:0xf
	v_lshlrev_b32_e32 v82, 16, v31
	v_and_b32_e32 v83, 0xffff0000, v31
	s_waitcnt lgkmcnt(0)
	v_add_f32_e32 v53, v53, v63
	s_nop 1
	v_mov_b32_dpp v63, v53 quad_perm:[1,0,3,2] row_mask:0xf bank_mask:0xf
	s_waitcnt lgkmcnt(0)
	v_add_f32_e32 v53, v53, v63
	v_fmamk_f32 v53, v53, 0x3a800000, v155
	v_cmp_gt_f32_e64 s[10:11], s69, v53
	v_mul_f32_e32 v63, 0x4b800000, v53
	s_nop 0
	v_cndmask_b32_e64 v53, v53, v63, s[10:11]
	v_rsq_f32_e32 v53, v53
	s_nop 0
	v_mul_f32_e32 v63, 0x45800000, v53
	v_cndmask_b32_e64 v78, v53, v63, s[10:11]
	v_pk_mul_f32 v[66:67], v[78:79], v[66:67] op_sel_hi:[0,1]
	v_pk_fma_f32 v[64:65], v[4:5], v[66:67], v[64:65]
	v_lshlrev_b32_e32 v66, 16, v17
	v_and_b32_e32 v67, 0xffff0000, v17
	v_pk_mul_f32 v[68:69], v[78:79], v[68:69] op_sel_hi:[0,1]
	v_pk_fma_f32 v[66:67], v[6:7], v[68:69], v[66:67]
	v_lshlrev_b32_e32 v68, 16, v18
	v_and_b32_e32 v69, 0xffff0000, v18
	v_pk_mul_f32 v[70:71], v[78:79], v[70:71] op_sel_hi:[0,1]
	v_pk_fma_f32 v[68:69], v[0:1], v[70:71], v[68:69]
	v_lshlrev_b32_e32 v70, 16, v19
	v_and_b32_e32 v71, 0xffff0000, v19
	v_pk_mul_f32 v[72:73], v[78:79], v[72:73] op_sel_hi:[0,1]
	v_pk_fma_f32 v[70:71], v[2:3], v[72:73], v[70:71]
	v_lshlrev_b32_e32 v72, 16, v20
	v_and_b32_e32 v73, 0xffff0000, v20
	v_pk_mul_f32 v[74:75], v[78:79], v[74:75] op_sel_hi:[0,1]
	v_pk_fma_f32 v[72:73], v[12:13], v[74:75], v[72:73]
	v_lshlrev_b32_e32 v74, 16, v21
	v_and_b32_e32 v75, 0xffff0000, v21
	v_pk_mul_f32 v[76:77], v[78:79], v[76:77] op_sel_hi:[0,1]
	v_pk_fma_f32 v[74:75], v[14:15], v[76:77], v[74:75]
	v_lshlrev_b32_e32 v76, 16, v22
	v_and_b32_e32 v77, 0xffff0000, v22
	v_pk_mul_f32 v[80:81], v[78:79], v[80:81] op_sel_hi:[0,1]
	v_pk_fma_f32 v[76:77], v[8:9], v[80:81], v[76:77]
	v_lshlrev_b32_e32 v80, 16, v23
	v_and_b32_e32 v81, 0xffff0000, v23
	v_pk_mul_f32 v[78:79], v[78:79], v[82:83] op_sel_hi:[0,1]
	v_ashrrev_i32_e32 v53, 31, v52
	v_pk_fma_f32 v[78:79], v[10:11], v[78:79], v[80:81]
	v_lshlrev_b64 v[80:81], 12, v[52:53]
	v_lshl_or_b32 v80, v54, 2, v80
	v_lshl_add_u64 v[80:81], s[86:87], 0, v[80:81]
	global_store_dwordx4 v[80:81], v[64:67], off
	global_store_dwordx4 v[80:81], v[68:71], off offset:16
	global_store_dwordx4 v[80:81], v[72:75], off offset:2048
	global_store_dwordx4 v[80:81], v[76:79], off offset:2064
	s_and_saveexec_b64 s[10:11], s[8:9]
	s_cbranch_execz .LBB0_1165
	v_add_u32_e32 v52, s19, v52
	v_cmp_gt_i32_e64 s[8:9], s33, v52
	s_and_saveexec_b64 s[6:7], s[8:9]
	s_cbranch_execz .LBB0_1164
	v_ashrrev_i32_e32 v53, 31, v52
	v_lshlrev_b64 v[24:25], 11, v[52:53]
	v_lshl_or_b32 v24, v54, 1, v24
	v_lshl_add_u64 v[20:21], s[56:57], 0, v[24:25]
	v_lshl_add_u64 v[28:29], s[20:21], 0, v[24:25]
	global_load_dwordx4 v[16:19], v[20:21], off
	s_nop 0
	global_load_dwordx4 v[20:23], v[20:21], off offset:1024
	s_nop 0
	global_load_dwordx4 v[24:27], v[28:29], off
	s_nop 0
	global_load_dwordx4 v[28:31], v[28:29], off offset:1024
	v_mov_b32_e32 v55, 0
	s_and_saveexec_b64 s[8:9], vcc
	s_cbranch_execz .LBB0_1163
	v_lshlrev_b64 v[52:53], 6, v[52:53]
	v_lshl_add_u64 v[52:53], v[48:49], 0, v[52:53]
	global_load_dword v55, v[52:53], off
	s_or_b64 exec, exec, s[8:9]
	s_or_b64 exec, exec, s[6:7]
	s_waitcnt vmcnt(5)
	s_branch .Le0_p8

.Le0_p5:
	s_mov_b32 s98, 0
	s_mov_b32 s99, -1
	v_mov_b32_e32 v250, v57
	v_mov_b32_e32 v55, v57
	s_nop 3
	v_permlane32_swap_b32_e32 v55, v250
	v_cndmask_b32_e64 v55, v250, v55, s[98:99]
	v_lshlrev_b32_e32 v70, 16, v24
	v_and_b32_e32 v71, 0xffff0000, v24
	v_lshlrev_b32_e32 v68, 16, v16
	v_and_b32_e32 v69, 0xffff0000, v16
	s_waitcnt lgkmcnt(0)
	v_add_f32_e32 v55, v57, v55
	ds_bpermute_b32 v65, v59, v55
	v_lshlrev_b32_e32 v72, 16, v25
	v_and_b32_e32 v73, 0xffff0000, v25
	v_lshlrev_b32_e32 v74, 16, v26
	v_and_b32_e32 v75, 0xffff0000, v26
	s_waitcnt lgkmcnt(0)
	v_add_f32_e32 v55, v55, v65
	s_nop 1
	v_mov_b32_dpp v65, v55 row_ror:8 row_mask:0xf bank_mask:0xf
	v_lshlrev_b32_e32 v76, 16, v27
	v_and_b32_e32 v77, 0xffff0000, v27
	v_lshlrev_b32_e32 v78, 16, v28
	v_and_b32_e32 v79, 0xffff0000, v28
	s_waitcnt lgkmcnt(0)
	v_add_f32_e32 v55, v55, v65
	s_nop 1
	v_mov_b32_dpp v65, v55 row_shl:4 row_mask:0xf bank_mask:0x5
	v_mov_b32_dpp v65, v55 row_shr:4 row_mask:0xf bank_mask:0xa
	v_lshlrev_b32_e32 v80, 16, v29
	v_and_b32_e32 v81, 0xffff0000, v29
	v_lshlrev_b32_e32 v82, 16, v30
	v_and_b32_e32 v83, 0xffff0000, v30
	s_waitcnt lgkmcnt(0)
	v_add_f32_e32 v55, v55, v65
	s_nop 1
	v_mov_b32_dpp v65, v55 quad_perm:[2,3,0,1] row_mask:0xf bank_mask:0xf
	v_lshlrev_b32_e32 v84, 16, v31
	v_and_b32_e32 v85, 0xffff0000, v31
	s_waitcnt lgkmcnt(0)
	v_add_f32_e32 v55, v55, v65
	s_nop 1
	v_mov_b32_dpp v65, v55 quad_perm:[1,0,3,2] row_mask:0xf bank_mask:0xf
	s_waitcnt lgkmcnt(0)
	v_add_f32_e32 v55, v55, v65
	v_fmamk_f32 v55, v55, 0x3a800000, v155
	v_cmp_gt_f32_e64 s[12:13], s69, v55
	v_mul_f32_e32 v65, 0x4b800000, v55
	s_nop 0
	v_cndmask_b32_e64 v55, v55, v65, s[12:13]
	v_rsq_f32_e32 v55, v55
	s_nop 0
	v_mul_f32_e32 v65, 0x45800000, v55
	v_cndmask_b32_e64 v66, v55, v65, s[12:13]
	v_pk_mul_f32 v[70:71], v[66:67], v[70:71] op_sel_hi:[0,1]
	v_pk_fma_f32 v[70:71], v[4:5], v[70:71], v[68:69]
	v_lshlrev_b32_e32 v68, 16, v17
	v_and_b32_e32 v69, 0xffff0000, v17
	v_pk_mul_f32 v[72:73], v[66:67], v[72:73] op_sel_hi:[0,1]
	v_pk_fma_f32 v[72:73], v[6:7], v[72:73], v[68:69]
	v_lshlrev_b32_e32 v68, 16, v18
	v_and_b32_e32 v69, 0xffff0000, v18
	v_pk_mul_f32 v[74:75], v[66:67], v[74:75] op_sel_hi:[0,1]
	v_pk_fma_f32 v[74:75], v[0:1], v[74:75], v[68:69]
	v_lshlrev_b32_e32 v68, 16, v19
	v_and_b32_e32 v69, 0xffff0000, v19
	v_pk_mul_f32 v[76:77], v[66:67], v[76:77] op_sel_hi:[0,1]
	v_pk_fma_f32 v[76:77], v[2:3], v[76:77], v[68:69]
	v_lshlrev_b32_e32 v68, 16, v20
	v_and_b32_e32 v69, 0xffff0000, v20
	v_pk_mul_f32 v[78:79], v[66:67], v[78:79] op_sel_hi:[0,1]
	v_pk_fma_f32 v[78:79], v[12:13], v[78:79], v[68:69]
	v_lshlrev_b32_e32 v68, 16, v21
	v_and_b32_e32 v69, 0xffff0000, v21
	v_pk_mul_f32 v[80:81], v[66:67], v[80:81] op_sel_hi:[0,1]
	v_pk_fma_f32 v[80:81], v[14:15], v[80:81], v[68:69]
	v_lshlrev_b32_e32 v68, 16, v22
	v_and_b32_e32 v69, 0xffff0000, v22
	v_pk_mul_f32 v[82:83], v[66:67], v[82:83] op_sel_hi:[0,1]
	v_pk_fma_f32 v[82:83], v[8:9], v[82:83], v[68:69]
	v_lshlrev_b32_e32 v68, 16, v23
	v_and_b32_e32 v69, 0xffff0000, v23
	v_pk_mul_f32 v[66:67], v[66:67], v[84:85] op_sel_hi:[0,1]
	v_pk_fma_f32 v[84:85], v[10:11], v[66:67], v[68:69]
	v_cvt_pk_bf16_f32 v66, v70, v71
	v_pk_mul_f32 v[70:71], v[70:71], v[70:71]
	v_cvt_pk_bf16_f32 v67, v72, v73
	v_pk_mul_f32 v[72:73], v[72:73], v[72:73]
	v_add_f32_e32 v65, v70, v71
	v_add_f32_e32 v65, v72, v65
	v_cvt_pk_bf16_f32 v68, v74, v75
	v_pk_mul_f32 v[74:75], v[74:75], v[74:75]
	v_add_f32_e32 v65, v73, v65
	v_ashrrev_i32_e32 v55, 31, v54
	v_add_f32_e32 v65, v74, v65
	v_lshlrev_b64 v[86:87], 11, v[54:55]
	v_cvt_pk_bf16_f32 v69, v76, v77
	v_pk_mul_f32 v[76:77], v[76:77], v[76:77]
	v_add_f32_e32 v65, v75, v65
	v_lshl_add_u64 v[86:87], v[48:49], 0, v[86:87]
	v_add_f32_e32 v65, v76, v65
	global_store_dwordx4 v[86:87], v[66:69], off
	v_add_f32_e32 v65, v77, v65
	s_nop 0
	v_cvt_pk_bf16_f32 v66, v78, v79
	v_pk_mul_f32 v[78:79], v[78:79], v[78:79]
	v_cvt_pk_bf16_f32 v67, v80, v81
	v_add_f32_e32 v65, v78, v65
	v_pk_mul_f32 v[80:81], v[80:81], v[80:81]
	v_add_f32_e32 v65, v79, v65
	v_add_f32_e32 v65, v80, v65
	v_cvt_pk_bf16_f32 v68, v82, v83
	v_pk_mul_f32 v[82:83], v[82:83], v[82:83]
	v_add_f32_e32 v65, v81, v65
	v_add_f32_e32 v65, v82, v65
	v_cvt_pk_bf16_f32 v69, v84, v85
	v_pk_mul_f32 v[84:85], v[84:85], v[84:85]
	v_add_f32_e32 v65, v83, v65
	v_add_f32_e32 v65, v84, v65
	v_add_f32_e32 v65, v85, v65
	global_store_dwordx4 v[86:87], v[66:69], off offset:1024
	s_mov_b32 s98, 0
	s_mov_b32 s99, -1
	v_mov_b32_e32 v250, v65
	v_mov_b32_e32 v66, v65
	s_nop 3
	v_permlane32_swap_b32_e32 v66, v250
	v_cndmask_b32_e64 v66, v250, v66, s[98:99]
	s_waitcnt lgkmcnt(0)
	v_add_f32_e32 v65, v65, v66
	ds_bpermute_b32 v66, v59, v65
	s_waitcnt lgkmcnt(0)
	v_add_f32_e32 v65, v65, v66
	s_nop 1
	v_mov_b32_dpp v66, v65 row_ror:8 row_mask:0xf bank_mask:0xf
	s_waitcnt lgkmcnt(0)
	v_add_f32_e32 v65, v65, v66
	s_nop 1
	v_mov_b32_dpp v66, v65 row_shl:4 row_mask:0xf bank_mask:0x5
	v_mov_b32_dpp v66, v65 row_shr:4 row_mask:0xf bank_mask:0xa
	s_waitcnt lgkmcnt(0)
	v_add_f32_e32 v65, v65, v66
	s_nop 1
	v_mov_b32_dpp v66, v65 quad_perm:[2,3,0,1] row_mask:0xf bank_mask:0xf
	s_waitcnt lgkmcnt(0)
	v_add_f32_e32 v65, v65, v66
	s_nop 1
	v_mov_b32_dpp v66, v65 quad_perm:[1,0,3,2] row_mask:0xf bank_mask:0xf
	s_and_saveexec_b64 s[6:7], s[8:9]
	s_cbranch_execz .LBB0_1188
	s_waitcnt lgkmcnt(0)
	v_add_f32_e32 v65, v65, v66
	v_fmamk_f32 v65, v65, 0x3a800000, v155
	v_mul_f32_e32 v66, 0x4b800000, v65
	v_cmp_gt_f32_e64 s[12:13], s69, v65
	s_nop 1
	v_cndmask_b32_e64 v65, v65, v66, s[12:13]
	v_rsq_f32_e32 v65, v65
	s_nop 0
	v_mul_f32_e32 v66, 0x45800000, v65
	v_cndmask_b32_e64 v65, v65, v66, s[12:13]
	v_lshl_add_u64 v[66:67], v[54:55], 2, s[62:63]
	global_store_dword v[66:67], v65, off

.Le0_p6:
	s_mov_b32 s98, 0
	s_mov_b32 s99, -1
	v_mov_b32_e32 v250, v64
	v_mov_b32_e32 v54, v64
	s_nop 3
	v_permlane32_swap_b32_e32 v54, v250
	v_cndmask_b32_e64 v54, v250, v54, s[98:99]
	v_lshlrev_b32_e32 v68, 16, v44
	v_and_b32_e32 v69, 0xffff0000, v44
	s_waitcnt lgkmcnt(1)
	v_lshlrev_b32_e32 v66, 16, v32
	v_and_b32_e32 v67, 0xffff0000, v32
	s_waitcnt lgkmcnt(0)
	v_add_f32_e32 v54, v64, v54
	ds_bpermute_b32 v55, v59, v54
	v_lshlrev_b64 v[84:85], 11, v[52:53]
	v_lshl_add_u64 v[84:85], v[48:49], 0, v[84:85]
	s_waitcnt lgkmcnt(0)
	v_add_f32_e32 v54, v54, v55
	s_nop 1
	v_mov_b32_dpp v55, v54 row_ror:8 row_mask:0xf bank_mask:0xf
	s_waitcnt lgkmcnt(0)
	v_add_f32_e32 v54, v54, v55
	s_nop 1
	v_mov_b32_dpp v55, v54 row_shl:4 row_mask:0xf bank_mask:0x5
	v_mov_b32_dpp v55, v54 row_shr:4 row_mask:0xf bank_mask:0xa
	s_waitcnt lgkmcnt(0)
	v_add_f32_e32 v54, v54, v55
	s_nop 1
	v_mov_b32_dpp v55, v54 quad_perm:[2,3,0,1] row_mask:0xf bank_mask:0xf
	s_waitcnt lgkmcnt(0)
	v_add_f32_e32 v54, v54, v55
	s_nop 1
	v_mov_b32_dpp v55, v54 quad_perm:[1,0,3,2] row_mask:0xf bank_mask:0xf
	s_waitcnt lgkmcnt(0)
	v_add_f32_e32 v54, v54, v55
	v_fmamk_f32 v54, v54, 0x3a800000, v155
	v_cmp_gt_f32_e64 s[10:11], s69, v54
	v_mul_f32_e32 v55, 0x4b800000, v54
	s_nop 0
	v_cndmask_b32_e64 v54, v54, v55, s[10:11]
	v_rsq_f32_e32 v54, v54
	s_nop 0
	v_mul_f32_e32 v55, 0x45800000, v54
	v_cndmask_b32_e64 v54, v54, v55, s[10:11]
	v_pk_mul_f32 v[68:69], v[54:55], v[68:69] op_sel_hi:[0,1]
	v_pk_fma_f32 v[70:71], v[4:5], v[68:69], v[66:67]
	v_lshlrev_b32_e32 v68, 16, v45
	v_and_b32_e32 v69, 0xffff0000, v45
	v_lshlrev_b32_e32 v66, 16, v33
	v_and_b32_e32 v67, 0xffff0000, v33
	v_pk_mul_f32 v[68:69], v[54:55], v[68:69] op_sel_hi:[0,1]
	v_pk_fma_f32 v[72:73], v[6:7], v[68:69], v[66:67]
	v_lshlrev_b32_e32 v68, 16, v46
	v_and_b32_e32 v69, 0xffff0000, v46
	v_lshlrev_b32_e32 v66, 16, v34
	v_and_b32_e32 v67, 0xffff0000, v34
	v_pk_mul_f32 v[68:69], v[54:55], v[68:69] op_sel_hi:[0,1]
	v_pk_fma_f32 v[74:75], v[0:1], v[68:69], v[66:67]
	v_lshlrev_b32_e32 v68, 16, v47
	v_and_b32_e32 v69, 0xffff0000, v47
	v_lshlrev_b32_e32 v66, 16, v35
	v_and_b32_e32 v67, 0xffff0000, v35
	v_pk_mul_f32 v[68:69], v[54:55], v[68:69] op_sel_hi:[0,1]
	v_pk_fma_f32 v[76:77], v[2:3], v[68:69], v[66:67]
	v_lshlrev_b32_e32 v68, 16, v40
	v_and_b32_e32 v69, 0xffff0000, v40
	v_lshlrev_b32_e32 v66, 16, v36
	v_and_b32_e32 v67, 0xffff0000, v36
	v_pk_mul_f32 v[68:69], v[54:55], v[68:69] op_sel_hi:[0,1]
	v_pk_fma_f32 v[78:79], v[12:13], v[68:69], v[66:67]
	v_lshlrev_b32_e32 v68, 16, v41
	v_and_b32_e32 v69, 0xffff0000, v41
	v_lshlrev_b32_e32 v66, 16, v37
	v_and_b32_e32 v67, 0xffff0000, v37
	v_pk_mul_f32 v[68:69], v[54:55], v[68:69] op_sel_hi:[0,1]
	v_pk_fma_f32 v[80:81], v[14:15], v[68:69], v[66:67]
	v_lshlrev_b32_e32 v68, 16, v42
	v_and_b32_e32 v69, 0xffff0000, v42
	v_lshlrev_b32_e32 v66, 16, v38
	v_and_b32_e32 v67, 0xffff0000, v38
	v_pk_mul_f32 v[68:69], v[54:55], v[68:69] op_sel_hi:[0,1]
	v_pk_fma_f32 v[82:83], v[8:9], v[68:69], v[66:67]
	v_lshlrev_b32_e32 v68, 16, v43
	v_and_b32_e32 v69, 0xffff0000, v43
	v_lshlrev_b32_e32 v66, 16, v39
	v_and_b32_e32 v67, 0xffff0000, v39
	v_pk_mul_f32 v[54:55], v[54:55], v[68:69] op_sel_hi:[0,1]
	v_pk_fma_f32 v[54:55], v[10:11], v[54:55], v[66:67]
	v_cvt_pk_bf16_f32 v66, v70, v71
	v_pk_mul_f32 v[70:71], v[70:71], v[70:71]
	v_cvt_pk_bf16_f32 v67, v72, v73
	v_pk_mul_f32 v[72:73], v[72:73], v[72:73]
	v_add_f32_e32 v65, v70, v71
	v_add_f32_e32 v65, v72, v65
	v_cvt_pk_bf16_f32 v68, v74, v75
	v_pk_mul_f32 v[74:75], v[74:75], v[74:75]
	v_add_f32_e32 v65, v73, v65
	v_add_f32_e32 v65, v74, v65
	v_cvt_pk_bf16_f32 v69, v76, v77
	v_pk_mul_f32 v[76:77], v[76:77], v[76:77]
	v_add_f32_e32 v65, v75, v65
	v_add_f32_e32 v65, v76, v65
	global_store_dwordx4 v[84:85], v[66:69], off
	v_add_f32_e32 v65, v77, v65
	s_nop 0
	v_cvt_pk_bf16_f32 v66, v78, v79
	v_pk_mul_f32 v[78:79], v[78:79], v[78:79]
	v_cvt_pk_bf16_f32 v67, v80, v81
	v_add_f32_e32 v65, v78, v65
	v_pk_mul_f32 v[80:81], v[80:81], v[80:81]
	v_add_f32_e32 v65, v79, v65
	v_add_f32_e32 v65, v80, v65
	v_cvt_pk_bf16_f32 v68, v82, v83
	v_pk_mul_f32 v[82:83], v[82:83], v[82:83]
	v_add_f32_e32 v65, v81, v65
	v_add_f32_e32 v65, v82, v65
	v_cvt_pk_bf16_f32 v69, v54, v55
	v_pk_mul_f32 v[54:55], v[54:55], v[54:55]
	v_add_f32_e32 v65, v83, v65
	v_add_f32_e32 v54, v54, v65
	v_add_f32_e32 v54, v55, v54
	s_mov_b32 s98, 0
	s_mov_b32 s99, -1
	v_mov_b32_e32 v250, v54
	v_mov_b32_e32 v55, v54
	s_nop 3
	v_permlane32_swap_b32_e32 v55, v250
	v_cndmask_b32_e64 v55, v250, v55, s[98:99]
	global_store_dwordx4 v[84:85], v[66:69], off offset:1024
	s_waitcnt lgkmcnt(0)
	v_add_f32_e32 v54, v54, v55
	ds_bpermute_b32 v55, v59, v54
	s_waitcnt lgkmcnt(0)
	v_add_f32_e32 v54, v54, v55
	s_nop 1
	v_mov_b32_dpp v55, v54 row_ror:8 row_mask:0xf bank_mask:0xf
	s_waitcnt lgkmcnt(0)
	v_add_f32_e32 v54, v54, v55
	s_nop 1
	v_mov_b32_dpp v55, v54 row_shl:4 row_mask:0xf bank_mask:0x5
	v_mov_b32_dpp v55, v54 row_shr:4 row_mask:0xf bank_mask:0xa
	s_waitcnt lgkmcnt(0)
	v_add_f32_e32 v54, v54, v55
	s_nop 1
	v_mov_b32_dpp v55, v54 quad_perm:[2,3,0,1] row_mask:0xf bank_mask:0xf
	s_waitcnt lgkmcnt(0)
	v_add_f32_e32 v54, v54, v55
	s_nop 1
	v_mov_b32_dpp v55, v54 quad_perm:[1,0,3,2] row_mask:0xf bank_mask:0xf
	s_and_saveexec_b64 s[6:7], s[8:9]
	s_cbranch_execz .LBB0_1180
	s_waitcnt lgkmcnt(0)
	v_add_f32_e32 v54, v54, v55
	v_fmamk_f32 v54, v54, 0x3a800000, v155
	v_mul_f32_e32 v55, 0x4b800000, v54
	v_cmp_gt_f32_e64 s[10:11], s69, v54
	s_nop 1
	v_cndmask_b32_e64 v54, v54, v55, s[10:11]
	v_rsq_f32_e32 v54, v54
	s_nop 0
	v_mul_f32_e32 v55, 0x45800000, v54
	v_cndmask_b32_e64 v65, v54, v55, s[10:11]
	v_lshl_add_u64 v[54:55], v[52:53], 2, s[62:63]
	global_store_dword v[54:55], v65, off
	s_branch .LBB0_1180
